# P4 epilogue: each lane loads two full rows of norm partials (8 loads instead of 32 redundant ones) and the lane quarters exchange row sums by permlane swaps; no per-row-group waits
# speedup vs baseline: 1.0047x; 1.0009x over previous
.LBB0_331:
	v_lshl_add_u32 v154, s8, 8, v1
	v_ashrrev_i32_e32 v155, 31, v154
	v_lshlrev_b64 v[156:157], 6, v[154:155]
	v_lshl_add_u64 v[156:157], s[30:31], 0, v[156:157]
	v_and_b32_e32 v250, 16, v0
	v_lshrrev_b32_e32 v251, 1, v250
	v_add_u32_e32 v250, v250, v251
	v_mov_b32_e32 v251, 0
	v_bfe_u32 v226, v0, 4, 2
	v_lshlrev_b32_e32 v226, 10, v226
	v_mov_b32_e32 v227, 0
	v_lshl_add_u64 v[242:243], v[156:157], 0, v[226:227]
	v_mov_b32_e32 v226, 0x2000
	v_lshl_add_u64 v[244:245], v[242:243], 0, v[226:227]
	global_load_dwordx4 v[194:197], v[242:243], off
	global_load_dwordx4 v[198:201], v[242:243], off offset:16
	global_load_dwordx4 v[202:205], v[242:243], off offset:32
	global_load_dwordx4 v[206:209], v[242:243], off offset:48
	global_load_dwordx4 v[210:213], v[244:245], off
	global_load_dwordx4 v[214:217], v[244:245], off offset:16
	global_load_dwordx4 v[218:221], v[244:245], off offset:32
	global_load_dwordx4 v[222:225], v[244:245], off offset:48
	s_waitcnt vmcnt(0)
	v_pk_add_f32 v[226:227], v[196:197], v[200:201]
	v_pk_add_f32 v[228:229], v[194:195], v[198:199]
	v_pk_add_f32 v[230:231], v[204:205], v[208:209]
	v_pk_add_f32 v[232:233], v[202:203], v[206:207]
	v_pk_add_f32 v[226:227], v[226:227], v[230:231]
	v_pk_add_f32 v[228:229], v[228:229], v[232:233]
	s_nop 0
	v_pk_mov_b32 v[230:231], v[228:229], v[226:227] op_sel:[1,0]
	v_mov_b32_e32 v229, v227
	v_pk_add_f32 v[228:229], v[230:231], v[228:229]
	s_nop 0
	v_add_f32_e32 v234, v228, v229
	v_mov_b32_e32 v235, v234
	s_nop 1
	v_permlane16_swap_b32_e32 v234, v235
	v_mov_b32_e32 v236, v234
	v_mov_b32_e32 v237, v235
	s_nop 1
	v_permlane32_swap_b32_e32 v234, v236
	v_permlane32_swap_b32_e32 v235, v237
	v_pk_add_f32 v[226:227], v[212:213], v[216:217]
	v_pk_add_f32 v[228:229], v[210:211], v[214:215]
	v_pk_add_f32 v[230:231], v[220:221], v[224:225]
	v_pk_add_f32 v[232:233], v[218:219], v[222:223]
	v_pk_add_f32 v[226:227], v[226:227], v[230:231]
	v_pk_add_f32 v[228:229], v[228:229], v[232:233]
	s_nop 0
	v_pk_mov_b32 v[230:231], v[228:229], v[226:227] op_sel:[1,0]
	v_mov_b32_e32 v229, v227
	v_pk_add_f32 v[228:229], v[230:231], v[228:229]
	s_nop 0
	v_add_f32_e32 v238, v228, v229
	v_mov_b32_e32 v239, v238
	s_nop 1
	v_permlane16_swap_b32_e32 v238, v239
	v_mov_b32_e32 v240, v238
	v_mov_b32_e32 v241, v239
	s_nop 1
	v_permlane32_swap_b32_e32 v238, v240
	v_permlane32_swap_b32_e32 v239, v241
	s_cmp_gt_i32 s18, 3
	s_cselect_b64 s[20:21], -1, 0
	s_cmp_lg_u32 s18, 4
	s_cselect_b64 s[22:23], -1, 0
	s_cmp_lt_i32 s18, 2
	s_cselect_b64 s[84:85], -1, 0
	s_cmp_gt_i32 s18, 1
	s_mov_b64 s[8:9], -1
	s_cselect_b64 s[38:39], -1, 0
	s_and_b64 vcc, exec, s[20:21]
	s_nop 0
	s_nop 0
	v_mov_b32_e32 v134, v234
	v_fmamk_f32 v134, v134, 0x3a800000, v162
	v_rsq_f32_e32 v134, v134
	s_nop 0
	v_pk_mul_f32 v[128:129], v[128:129], v[134:135] op_sel_hi:[1,0]
	v_pk_mul_f32 v[126:127], v[126:127], v[134:135] op_sel_hi:[1,0]
	v_pk_mul_f32 v[124:125], v[124:125], v[134:135] op_sel_hi:[1,0]
	v_pk_mul_f32 v[122:123], v[122:123], v[134:135] op_sel_hi:[1,0]
	v_pk_mul_f32 v[120:121], v[120:121], v[134:135] op_sel_hi:[1,0]
	v_pk_mul_f32 v[118:119], v[118:119], v[134:135] op_sel_hi:[1,0]
	v_pk_mul_f32 v[116:117], v[116:117], v[134:135] op_sel_hi:[1,0]
	v_pk_mul_f32 v[114:115], v[114:115], v[134:135] op_sel_hi:[1,0]
	s_cbranch_vccz .LBB0_343
	v_mul_f32_e32 v134, v127, v127
	v_mul_f32_e32 v156, v129, v129
	v_fmac_f32_e32 v134, v126, v126
	v_fmac_f32_e32 v156, v128, v128
	v_add_f32_e32 v166, v134, v156
	s_and_b64 vcc, exec, s[22:23]
	v_lshlrev_b64 v[156:157], 9, v[154:155]
	v_mul_f32_e32 v167, v123, v123
	v_mul_f32_e32 v168, v125, v125
	s_cbranch_vccz .LBB0_338
	v_fma_f32 v134, v122, v122, v167
	v_fma_f32 v169, v124, v124, v168
	v_and_b32_e32 v173, 64, v163
	v_add_f32_e32 v134, v134, v169
	v_xor_b32_e32 v169, 16, v163
	v_add_u32_e32 v176, 64, v173
	v_cmp_lt_i32_e32 vcc, v169, v176
	v_add_f32_e32 v134, v166, v134
	v_lshlrev_b64 v[174:175], 8, v[154:155]
	v_cndmask_b32_e32 v169, v163, v169, vcc
	v_lshlrev_b32_e32 v169, 2, v169
	ds_bpermute_b32 v169, v169, v134
	v_lshl_add_u64 v[170:171], v[140:141], 0, v[156:157]
	v_lshl_add_u64 v[174:175], v[142:143], 0, v[174:175]
	global_store_dwordx4 v[170:171], v[126:129], off
	v_cvt_pk_bf16_f32 v172, v126, v127
	s_waitcnt lgkmcnt(0)
	v_add_f32_e32 v134, v134, v169
	v_xor_b32_e32 v169, 32, v163
	v_cmp_lt_i32_e32 vcc, v169, v176
	v_cvt_pk_bf16_f32 v173, v128, v129
	global_store_dwordx2 v[174:175], v[172:173], off
	global_store_dwordx4 v[170:171], v[122:125], off offset:64
	v_cndmask_b32_e32 v169, v163, v169, vcc
	v_lshlrev_b32_e32 v169, 2, v169
	ds_bpermute_b32 v169, v169, v134
	v_cvt_pk_bf16_f32 v170, v122, v123
	v_cvt_pk_bf16_f32 v171, v124, v125
	global_store_dwordx2 v[174:175], v[170:171], off offset:32
	s_and_saveexec_b64 s[8:9], s[4:5]
	s_cbranch_execz .LBB0_335
	v_lshlrev_b64 v[170:171], 5, v[154:155]
	v_lshl_add_u64 v[170:171], s[42:43], 0, v[170:171]
	s_waitcnt lgkmcnt(0)
	v_add_f32_e32 v134, v134, v169
	global_store_dword v[170:171], v134, off offset:16

.LBB0_353:
	v_or_b32_e32 v114, 16, v154
	v_ashrrev_i32_e32 v115, 31, v114
	v_lshlrev_b64 v[116:117], 6, v[114:115]
	v_lshl_add_u64 v[128:129], s[30:31], 0, v[116:117]
	s_waitcnt lgkmcnt(0)
	v_cndmask_b32_e64 v128, 0, 1, s[20:21]
	s_mov_b64 s[14:15], -1
	v_cmp_ne_u32_e64 s[12:13], 1, v128
	s_andn2_b64 vcc, exec, s[20:21]
	s_nop 0
	s_nop 0
	v_mov_b32_e32 v116, v235
	v_fmamk_f32 v116, v116, 0x3a800000, v162
	v_rsq_f32_e32 v116, v116
	v_cndmask_b32_e64 v117, 0, 1, s[22:23]
	v_cmp_ne_u32_e64 s[10:11], 1, v117
	v_pk_mul_f32 v[112:113], v[112:113], v[116:117] op_sel_hi:[1,0]
	v_pk_mul_f32 v[110:111], v[110:111], v[116:117] op_sel_hi:[1,0]
	v_pk_mul_f32 v[108:109], v[108:109], v[116:117] op_sel_hi:[1,0]
	v_pk_mul_f32 v[106:107], v[106:107], v[116:117] op_sel_hi:[1,0]
	v_pk_mul_f32 v[104:105], v[104:105], v[116:117] op_sel_hi:[1,0]
	v_pk_mul_f32 v[102:103], v[102:103], v[116:117] op_sel_hi:[1,0]
	v_pk_mul_f32 v[100:101], v[100:101], v[116:117] op_sel_hi:[1,0]
	v_pk_mul_f32 v[98:99], v[98:99], v[116:117] op_sel_hi:[1,0]
	s_cbranch_vccnz .LBB0_365
	v_mul_f32_e32 v116, v111, v111
	v_mul_f32_e32 v117, v113, v113
	v_fmac_f32_e32 v116, v110, v110
	v_fmac_f32_e32 v117, v112, v112
	v_add_f32_e32 v118, v116, v117
	s_and_b64 vcc, exec, s[10:11]
	v_lshlrev_b64 v[116:117], 9, v[114:115]
	v_mul_f32_e32 v119, v107, v107
	v_mul_f32_e32 v120, v109, v109
	s_cbranch_vccnz .LBB0_360
	v_fma_f32 v121, v106, v106, v119
	v_fma_f32 v123, v108, v108, v120
	v_and_b32_e32 v126, 64, v163
	v_add_f32_e32 v121, v121, v123
	v_xor_b32_e32 v123, 16, v163
	v_add_u32_e32 v128, 64, v126
	v_cmp_lt_i32_e32 vcc, v123, v128
	v_add_f32_e32 v121, v118, v121
	v_lshl_add_u64 v[124:125], v[140:141], 0, v[116:117]
	v_cndmask_b32_e32 v123, v163, v123, vcc
	v_lshlrev_b32_e32 v123, 2, v123
	ds_bpermute_b32 v129, v123, v121
	v_lshlrev_b64 v[126:127], 8, v[114:115]
	global_store_dwordx4 v[124:125], v[110:113], off
	v_cvt_pk_bf16_f32 v122, v110, v111
	v_lshl_add_u64 v[126:127], v[142:143], 0, v[126:127]
	v_cvt_pk_bf16_f32 v123, v112, v113
	global_store_dwordx2 v[126:127], v[122:123], off
	v_xor_b32_e32 v122, 32, v163
	v_cmp_lt_i32_e32 vcc, v122, v128
	s_waitcnt lgkmcnt(0)
	v_add_f32_e32 v121, v121, v129
	global_store_dwordx4 v[124:125], v[106:109], off offset:64
	v_cndmask_b32_e32 v122, v163, v122, vcc
	v_lshlrev_b32_e32 v122, 2, v122
	ds_bpermute_b32 v122, v122, v121
	v_cvt_pk_bf16_f32 v124, v106, v107
	v_cvt_pk_bf16_f32 v125, v108, v109
	global_store_dwordx2 v[126:127], v[124:125], off offset:32
	s_and_saveexec_b64 s[14:15], s[4:5]
	s_cbranch_execz .LBB0_357
	v_lshlrev_b64 v[124:125], 5, v[114:115]
	v_lshl_add_u64 v[124:125], s[42:43], 0, v[124:125]
	s_waitcnt lgkmcnt(0)
	v_add_f32_e32 v121, v121, v122
	global_store_dword v[124:125], v121, off offset:16

.LBB0_375:
	v_or_b32_e32 v98, 32, v154
	v_ashrrev_i32_e32 v99, 31, v98
	v_lshlrev_b64 v[100:101], 6, v[98:99]
	v_lshl_add_u64 v[112:113], s[30:31], 0, v[100:101]
	s_nop 0
	s_and_b64 vcc, exec, s[12:13]
	s_mov_b64 s[14:15], -1
	s_nop 0
	s_nop 0
	v_mov_b32_e32 v100, v236
	v_fmamk_f32 v100, v100, 0x3a800000, v162
	v_rsq_f32_e32 v100, v100
	s_nop 0
	v_pk_mul_f32 v[96:97], v[96:97], v[100:101] op_sel_hi:[1,0]
	v_pk_mul_f32 v[94:95], v[94:95], v[100:101] op_sel_hi:[1,0]
	v_pk_mul_f32 v[92:93], v[92:93], v[100:101] op_sel_hi:[1,0]
	v_pk_mul_f32 v[90:91], v[90:91], v[100:101] op_sel_hi:[1,0]
	v_pk_mul_f32 v[88:89], v[88:89], v[100:101] op_sel_hi:[1,0]
	v_pk_mul_f32 v[86:87], v[86:87], v[100:101] op_sel_hi:[1,0]
	v_pk_mul_f32 v[84:85], v[84:85], v[100:101] op_sel_hi:[1,0]
	v_pk_mul_f32 v[82:83], v[82:83], v[100:101] op_sel_hi:[1,0]
	s_cbranch_vccnz .LBB0_387
	v_mul_f32_e32 v100, v95, v95
	v_mul_f32_e32 v101, v97, v97
	v_fmac_f32_e32 v100, v94, v94
	v_fmac_f32_e32 v101, v96, v96
	v_add_f32_e32 v102, v100, v101
	s_and_b64 vcc, exec, s[10:11]
	v_lshlrev_b64 v[100:101], 9, v[98:99]
	v_mul_f32_e32 v103, v91, v91
	v_mul_f32_e32 v104, v93, v93
	s_cbranch_vccnz .LBB0_382
	v_fma_f32 v105, v90, v90, v103
	v_fma_f32 v107, v92, v92, v104
	v_and_b32_e32 v110, 64, v163
	v_add_f32_e32 v105, v105, v107
	v_xor_b32_e32 v107, 16, v163
	v_add_u32_e32 v112, 64, v110
	v_cmp_lt_i32_e32 vcc, v107, v112
	v_add_f32_e32 v105, v102, v105
	v_lshl_add_u64 v[108:109], v[140:141], 0, v[100:101]
	v_cndmask_b32_e32 v107, v163, v107, vcc
	v_lshlrev_b32_e32 v107, 2, v107
	ds_bpermute_b32 v113, v107, v105
	v_lshlrev_b64 v[110:111], 8, v[98:99]
	global_store_dwordx4 v[108:109], v[94:97], off
	v_cvt_pk_bf16_f32 v106, v94, v95
	v_lshl_add_u64 v[110:111], v[142:143], 0, v[110:111]
	v_cvt_pk_bf16_f32 v107, v96, v97
	global_store_dwordx2 v[110:111], v[106:107], off
	v_xor_b32_e32 v106, 32, v163
	v_cmp_lt_i32_e32 vcc, v106, v112
	s_waitcnt lgkmcnt(0)
	v_add_f32_e32 v105, v105, v113
	global_store_dwordx4 v[108:109], v[90:93], off offset:64
	v_cndmask_b32_e32 v106, v163, v106, vcc
	v_lshlrev_b32_e32 v106, 2, v106
	ds_bpermute_b32 v106, v106, v105
	v_cvt_pk_bf16_f32 v108, v90, v91
	v_cvt_pk_bf16_f32 v109, v92, v93
	global_store_dwordx2 v[110:111], v[108:109], off offset:32
	s_and_saveexec_b64 s[14:15], s[4:5]
	s_cbranch_execz .LBB0_379
	v_lshlrev_b64 v[108:109], 5, v[98:99]
	v_lshl_add_u64 v[108:109], s[42:43], 0, v[108:109]
	s_waitcnt lgkmcnt(0)
	v_add_f32_e32 v105, v105, v106
	global_store_dword v[108:109], v105, off offset:16

.LBB0_397:
	v_or_b32_e32 v82, 48, v154
	v_ashrrev_i32_e32 v83, 31, v82
	v_lshlrev_b64 v[84:85], 6, v[82:83]
	v_lshl_add_u64 v[96:97], s[30:31], 0, v[84:85]
	s_nop 0
	s_and_b64 vcc, exec, s[12:13]
	s_mov_b64 s[14:15], -1
	s_nop 0
	s_nop 0
	v_mov_b32_e32 v84, v237
	v_fmamk_f32 v84, v84, 0x3a800000, v162
	v_rsq_f32_e32 v84, v84
	s_nop 0
	v_pk_mul_f32 v[80:81], v[80:81], v[84:85] op_sel_hi:[1,0]
	v_pk_mul_f32 v[78:79], v[78:79], v[84:85] op_sel_hi:[1,0]
	v_pk_mul_f32 v[76:77], v[76:77], v[84:85] op_sel_hi:[1,0]
	v_pk_mul_f32 v[74:75], v[74:75], v[84:85] op_sel_hi:[1,0]
	v_pk_mul_f32 v[72:73], v[72:73], v[84:85] op_sel_hi:[1,0]
	v_pk_mul_f32 v[70:71], v[70:71], v[84:85] op_sel_hi:[1,0]
	v_pk_mul_f32 v[68:69], v[68:69], v[84:85] op_sel_hi:[1,0]
	v_pk_mul_f32 v[66:67], v[66:67], v[84:85] op_sel_hi:[1,0]
	s_cbranch_vccnz .LBB0_409
	v_mul_f32_e32 v84, v79, v79
	v_mul_f32_e32 v85, v81, v81
	v_fmac_f32_e32 v84, v78, v78
	v_fmac_f32_e32 v85, v80, v80
	v_add_f32_e32 v86, v84, v85
	s_and_b64 vcc, exec, s[10:11]
	v_lshlrev_b64 v[84:85], 9, v[82:83]
	v_mul_f32_e32 v87, v75, v75
	v_mul_f32_e32 v88, v77, v77
	s_cbranch_vccnz .LBB0_404
	v_fma_f32 v89, v74, v74, v87
	v_fma_f32 v91, v76, v76, v88
	v_and_b32_e32 v94, 64, v163
	v_add_f32_e32 v89, v89, v91
	v_xor_b32_e32 v91, 16, v163
	v_add_u32_e32 v96, 64, v94
	v_cmp_lt_i32_e32 vcc, v91, v96
	v_add_f32_e32 v89, v86, v89
	v_lshl_add_u64 v[92:93], v[140:141], 0, v[84:85]
	v_cndmask_b32_e32 v91, v163, v91, vcc
	v_lshlrev_b32_e32 v91, 2, v91
	ds_bpermute_b32 v97, v91, v89
	v_lshlrev_b64 v[94:95], 8, v[82:83]
	global_store_dwordx4 v[92:93], v[78:81], off
	v_cvt_pk_bf16_f32 v90, v78, v79
	v_lshl_add_u64 v[94:95], v[142:143], 0, v[94:95]
	v_cvt_pk_bf16_f32 v91, v80, v81
	global_store_dwordx2 v[94:95], v[90:91], off
	v_xor_b32_e32 v90, 32, v163
	v_cmp_lt_i32_e32 vcc, v90, v96
	s_waitcnt lgkmcnt(0)
	v_add_f32_e32 v89, v89, v97
	global_store_dwordx4 v[92:93], v[74:77], off offset:64
	v_cndmask_b32_e32 v90, v163, v90, vcc
	v_lshlrev_b32_e32 v90, 2, v90
	ds_bpermute_b32 v90, v90, v89
	v_cvt_pk_bf16_f32 v92, v74, v75
	v_cvt_pk_bf16_f32 v93, v76, v77
	global_store_dwordx2 v[94:95], v[92:93], off offset:32
	s_and_saveexec_b64 s[14:15], s[4:5]
	s_cbranch_execz .LBB0_401
	v_lshlrev_b64 v[92:93], 5, v[82:83]
	v_lshl_add_u64 v[92:93], s[42:43], 0, v[92:93]
	s_waitcnt lgkmcnt(0)
	v_add_f32_e32 v89, v89, v90
	global_store_dword v[92:93], v89, off offset:16

.LBB0_419:
	v_add_u32_e32 v66, 0x80, v154
	v_ashrrev_i32_e32 v67, 31, v66
	v_lshlrev_b64 v[68:69], 6, v[66:67]
	v_lshl_add_u64 v[80:81], s[30:31], 0, v[68:69]
	s_nop 0
	s_and_b64 vcc, exec, s[12:13]
	s_mov_b64 s[14:15], -1
	s_nop 0
	s_nop 0
	v_mov_b32_e32 v68, v238
	v_fmamk_f32 v68, v68, 0x3a800000, v162
	v_rsq_f32_e32 v68, v68
	s_nop 0
	v_pk_mul_f32 v[64:65], v[64:65], v[68:69] op_sel_hi:[1,0]
	v_pk_mul_f32 v[62:63], v[62:63], v[68:69] op_sel_hi:[1,0]
	v_pk_mul_f32 v[60:61], v[60:61], v[68:69] op_sel_hi:[1,0]
	v_pk_mul_f32 v[58:59], v[58:59], v[68:69] op_sel_hi:[1,0]
	v_pk_mul_f32 v[56:57], v[56:57], v[68:69] op_sel_hi:[1,0]
	v_pk_mul_f32 v[54:55], v[54:55], v[68:69] op_sel_hi:[1,0]
	v_pk_mul_f32 v[52:53], v[52:53], v[68:69] op_sel_hi:[1,0]
	v_pk_mul_f32 v[50:51], v[50:51], v[68:69] op_sel_hi:[1,0]
	s_cbranch_vccnz .LBB0_431
	v_mul_f32_e32 v68, v63, v63
	v_mul_f32_e32 v69, v65, v65
	v_fmac_f32_e32 v68, v62, v62
	v_fmac_f32_e32 v69, v64, v64
	v_add_f32_e32 v70, v68, v69
	s_and_b64 vcc, exec, s[10:11]
	v_lshlrev_b64 v[68:69], 9, v[66:67]
	v_mul_f32_e32 v71, v59, v59
	v_mul_f32_e32 v72, v61, v61
	s_cbranch_vccnz .LBB0_426
	v_fma_f32 v73, v58, v58, v71
	v_fma_f32 v75, v60, v60, v72
	v_and_b32_e32 v78, 64, v163
	v_add_f32_e32 v73, v73, v75
	v_xor_b32_e32 v75, 16, v163
	v_add_u32_e32 v80, 64, v78
	v_cmp_lt_i32_e32 vcc, v75, v80
	v_add_f32_e32 v73, v70, v73
	v_lshl_add_u64 v[76:77], v[140:141], 0, v[68:69]
	v_cndmask_b32_e32 v75, v163, v75, vcc
	v_lshlrev_b32_e32 v75, 2, v75
	ds_bpermute_b32 v81, v75, v73
	v_lshlrev_b64 v[78:79], 8, v[66:67]
	global_store_dwordx4 v[76:77], v[62:65], off
	v_cvt_pk_bf16_f32 v74, v62, v63
	v_lshl_add_u64 v[78:79], v[142:143], 0, v[78:79]
	v_cvt_pk_bf16_f32 v75, v64, v65
	global_store_dwordx2 v[78:79], v[74:75], off
	v_xor_b32_e32 v74, 32, v163
	v_cmp_lt_i32_e32 vcc, v74, v80
	s_waitcnt lgkmcnt(0)
	v_add_f32_e32 v73, v73, v81
	global_store_dwordx4 v[76:77], v[58:61], off offset:64
	v_cndmask_b32_e32 v74, v163, v74, vcc
	v_lshlrev_b32_e32 v74, 2, v74
	ds_bpermute_b32 v74, v74, v73
	v_cvt_pk_bf16_f32 v76, v58, v59
	v_cvt_pk_bf16_f32 v77, v60, v61
	global_store_dwordx2 v[78:79], v[76:77], off offset:32
	s_and_saveexec_b64 s[14:15], s[4:5]
	s_cbranch_execz .LBB0_423
	v_lshlrev_b64 v[76:77], 5, v[66:67]
	v_lshl_add_u64 v[76:77], s[42:43], 0, v[76:77]
	s_waitcnt lgkmcnt(0)
	v_add_f32_e32 v73, v73, v74
	global_store_dword v[76:77], v73, off offset:16

.LBB0_441:
	v_add_u32_e32 v50, 0x90, v154
	v_ashrrev_i32_e32 v51, 31, v50
	v_lshlrev_b64 v[52:53], 6, v[50:51]
	v_lshl_add_u64 v[64:65], s[30:31], 0, v[52:53]
	s_nop 0
	s_and_b64 vcc, exec, s[12:13]
	s_mov_b64 s[14:15], -1
	s_nop 0
	s_nop 0
	v_mov_b32_e32 v52, v239
	v_fmamk_f32 v52, v52, 0x3a800000, v162
	v_rsq_f32_e32 v52, v52
	s_nop 0
	v_pk_mul_f32 v[48:49], v[48:49], v[52:53] op_sel_hi:[1,0]
	v_pk_mul_f32 v[46:47], v[46:47], v[52:53] op_sel_hi:[1,0]
	v_pk_mul_f32 v[44:45], v[44:45], v[52:53] op_sel_hi:[1,0]
	v_pk_mul_f32 v[42:43], v[42:43], v[52:53] op_sel_hi:[1,0]
	v_pk_mul_f32 v[40:41], v[40:41], v[52:53] op_sel_hi:[1,0]
	v_pk_mul_f32 v[38:39], v[38:39], v[52:53] op_sel_hi:[1,0]
	v_pk_mul_f32 v[36:37], v[36:37], v[52:53] op_sel_hi:[1,0]
	v_pk_mul_f32 v[34:35], v[34:35], v[52:53] op_sel_hi:[1,0]
	s_cbranch_vccnz .LBB0_453
	v_mul_f32_e32 v52, v47, v47
	v_mul_f32_e32 v53, v49, v49
	v_fmac_f32_e32 v52, v46, v46
	v_fmac_f32_e32 v53, v48, v48
	v_add_f32_e32 v54, v52, v53
	s_and_b64 vcc, exec, s[10:11]
	v_lshlrev_b64 v[52:53], 9, v[50:51]
	v_mul_f32_e32 v55, v43, v43
	v_mul_f32_e32 v56, v45, v45
	s_cbranch_vccnz .LBB0_448
	v_fma_f32 v57, v42, v42, v55
	v_fma_f32 v59, v44, v44, v56
	v_and_b32_e32 v62, 64, v163
	v_add_f32_e32 v57, v57, v59
	v_xor_b32_e32 v59, 16, v163
	v_add_u32_e32 v64, 64, v62
	v_cmp_lt_i32_e32 vcc, v59, v64
	v_add_f32_e32 v57, v54, v57
	v_lshl_add_u64 v[60:61], v[140:141], 0, v[52:53]
	v_cndmask_b32_e32 v59, v163, v59, vcc
	v_lshlrev_b32_e32 v59, 2, v59
	ds_bpermute_b32 v65, v59, v57
	v_lshlrev_b64 v[62:63], 8, v[50:51]
	global_store_dwordx4 v[60:61], v[46:49], off
	v_cvt_pk_bf16_f32 v58, v46, v47
	v_lshl_add_u64 v[62:63], v[142:143], 0, v[62:63]
	v_cvt_pk_bf16_f32 v59, v48, v49
	global_store_dwordx2 v[62:63], v[58:59], off
	v_xor_b32_e32 v58, 32, v163
	v_cmp_lt_i32_e32 vcc, v58, v64
	s_waitcnt lgkmcnt(0)
	v_add_f32_e32 v57, v57, v65
	global_store_dwordx4 v[60:61], v[42:45], off offset:64
	v_cndmask_b32_e32 v58, v163, v58, vcc
	v_lshlrev_b32_e32 v58, 2, v58
	ds_bpermute_b32 v58, v58, v57
	v_cvt_pk_bf16_f32 v60, v42, v43
	v_cvt_pk_bf16_f32 v61, v44, v45
	global_store_dwordx2 v[62:63], v[60:61], off offset:32
	s_and_saveexec_b64 s[14:15], s[4:5]
	s_cbranch_execz .LBB0_445
	v_lshlrev_b64 v[60:61], 5, v[50:51]
	v_lshl_add_u64 v[60:61], s[42:43], 0, v[60:61]
	s_waitcnt lgkmcnt(0)
	v_add_f32_e32 v57, v57, v58
	global_store_dword v[60:61], v57, off offset:16

.LBB0_463:
	v_add_u32_e32 v34, 0xa0, v154
	v_ashrrev_i32_e32 v35, 31, v34
	v_lshlrev_b64 v[36:37], 6, v[34:35]
	v_lshl_add_u64 v[48:49], s[30:31], 0, v[36:37]
	s_nop 0
	s_and_b64 vcc, exec, s[12:13]
	s_mov_b64 s[14:15], -1
	s_nop 0
	s_nop 0
	v_mov_b32_e32 v36, v240
	v_fmamk_f32 v36, v36, 0x3a800000, v162
	v_rsq_f32_e32 v36, v36
	s_nop 0
	v_pk_mul_f32 v[32:33], v[32:33], v[36:37] op_sel_hi:[1,0]
	v_pk_mul_f32 v[30:31], v[30:31], v[36:37] op_sel_hi:[1,0]
	v_pk_mul_f32 v[28:29], v[28:29], v[36:37] op_sel_hi:[1,0]
	v_pk_mul_f32 v[26:27], v[26:27], v[36:37] op_sel_hi:[1,0]
	v_pk_mul_f32 v[24:25], v[24:25], v[36:37] op_sel_hi:[1,0]
	v_pk_mul_f32 v[22:23], v[22:23], v[36:37] op_sel_hi:[1,0]
	v_pk_mul_f32 v[20:21], v[20:21], v[36:37] op_sel_hi:[1,0]
	v_pk_mul_f32 v[18:19], v[18:19], v[36:37] op_sel_hi:[1,0]
	s_cbranch_vccnz .LBB0_475
	v_mul_f32_e32 v36, v31, v31
	v_mul_f32_e32 v37, v33, v33
	v_fmac_f32_e32 v36, v30, v30
	v_fmac_f32_e32 v37, v32, v32
	v_add_f32_e32 v38, v36, v37
	s_and_b64 vcc, exec, s[10:11]
	v_lshlrev_b64 v[36:37], 9, v[34:35]
	v_mul_f32_e32 v39, v27, v27
	v_mul_f32_e32 v40, v29, v29
	s_cbranch_vccnz .LBB0_470
	v_fma_f32 v41, v26, v26, v39
	v_fma_f32 v43, v28, v28, v40
	v_and_b32_e32 v46, 64, v163
	v_add_f32_e32 v41, v41, v43
	v_xor_b32_e32 v43, 16, v163
	v_add_u32_e32 v48, 64, v46
	v_cmp_lt_i32_e32 vcc, v43, v48
	v_add_f32_e32 v41, v38, v41
	v_lshl_add_u64 v[44:45], v[140:141], 0, v[36:37]
	v_cndmask_b32_e32 v43, v163, v43, vcc
	v_lshlrev_b32_e32 v43, 2, v43
	ds_bpermute_b32 v49, v43, v41
	v_lshlrev_b64 v[46:47], 8, v[34:35]
	global_store_dwordx4 v[44:45], v[30:33], off
	v_cvt_pk_bf16_f32 v42, v30, v31
	v_lshl_add_u64 v[46:47], v[142:143], 0, v[46:47]
	v_cvt_pk_bf16_f32 v43, v32, v33
	global_store_dwordx2 v[46:47], v[42:43], off
	v_xor_b32_e32 v42, 32, v163
	v_cmp_lt_i32_e32 vcc, v42, v48
	s_waitcnt lgkmcnt(0)
	v_add_f32_e32 v41, v41, v49
	global_store_dwordx4 v[44:45], v[26:29], off offset:64
	v_cndmask_b32_e32 v42, v163, v42, vcc
	v_lshlrev_b32_e32 v42, 2, v42
	ds_bpermute_b32 v42, v42, v41
	v_cvt_pk_bf16_f32 v44, v26, v27
	v_cvt_pk_bf16_f32 v45, v28, v29
	global_store_dwordx2 v[46:47], v[44:45], off offset:32
	s_and_saveexec_b64 s[14:15], s[4:5]
	s_cbranch_execz .LBB0_467
	v_lshlrev_b64 v[44:45], 5, v[34:35]
	v_lshl_add_u64 v[44:45], s[42:43], 0, v[44:45]
	s_waitcnt lgkmcnt(0)
	v_add_f32_e32 v41, v41, v42
	global_store_dword v[44:45], v41, off offset:16

.LBB0_485:
	v_add_u32_e32 v18, 0xb0, v154
	v_ashrrev_i32_e32 v19, 31, v18
	v_lshlrev_b64 v[20:21], 6, v[18:19]
	v_lshl_add_u64 v[32:33], s[30:31], 0, v[20:21]
	s_nop 0
	s_and_b64 vcc, exec, s[12:13]
	s_mov_b64 s[12:13], -1
	s_nop 0
	s_nop 0
	v_mov_b32_e32 v20, v241
	v_fmamk_f32 v20, v20, 0x3a800000, v162
	v_rsq_f32_e32 v20, v20
	s_nop 0
	v_pk_mul_f32 v[16:17], v[16:17], v[20:21] op_sel_hi:[1,0]
	v_pk_mul_f32 v[14:15], v[14:15], v[20:21] op_sel_hi:[1,0]
	v_pk_mul_f32 v[12:13], v[12:13], v[20:21] op_sel_hi:[1,0]
	v_pk_mul_f32 v[10:11], v[10:11], v[20:21] op_sel_hi:[1,0]
	v_pk_mul_f32 v[8:9], v[8:9], v[20:21] op_sel_hi:[1,0]
	v_pk_mul_f32 v[6:7], v[6:7], v[20:21] op_sel_hi:[1,0]
	v_pk_mul_f32 v[4:5], v[4:5], v[20:21] op_sel_hi:[1,0]
	v_pk_mul_f32 v[2:3], v[2:3], v[20:21] op_sel_hi:[1,0]
	s_cbranch_vccnz .LBB0_498
	v_mul_f32_e32 v20, v15, v15
	v_mul_f32_e32 v21, v17, v17
	v_fmac_f32_e32 v20, v14, v14
	v_fmac_f32_e32 v21, v16, v16
	v_add_f32_e32 v22, v20, v21
	s_and_b64 vcc, exec, s[10:11]
	v_lshlrev_b64 v[20:21], 9, v[18:19]
	v_mul_f32_e32 v23, v11, v11
	v_mul_f32_e32 v24, v13, v13
	s_cbranch_vccnz .LBB0_492
	v_fma_f32 v25, v10, v10, v23
	v_fma_f32 v27, v12, v12, v24
	v_and_b32_e32 v30, 64, v163
	v_add_f32_e32 v25, v25, v27
	v_xor_b32_e32 v27, 16, v163
	v_add_u32_e32 v32, 64, v30
	v_cmp_lt_i32_e32 vcc, v27, v32
	v_add_f32_e32 v25, v22, v25
	v_lshl_add_u64 v[28:29], v[140:141], 0, v[20:21]
	v_cndmask_b32_e32 v27, v163, v27, vcc
	v_lshlrev_b32_e32 v27, 2, v27
	ds_bpermute_b32 v33, v27, v25
	v_lshlrev_b64 v[30:31], 8, v[18:19]
	global_store_dwordx4 v[28:29], v[14:17], off
	v_cvt_pk_bf16_f32 v26, v14, v15
	v_lshl_add_u64 v[30:31], v[142:143], 0, v[30:31]
	v_cvt_pk_bf16_f32 v27, v16, v17
	global_store_dwordx2 v[30:31], v[26:27], off
	v_xor_b32_e32 v26, 32, v163
	v_cmp_lt_i32_e32 vcc, v26, v32
	s_waitcnt lgkmcnt(0)
	v_add_f32_e32 v25, v25, v33
	global_store_dwordx4 v[28:29], v[10:13], off offset:64
	v_cndmask_b32_e32 v26, v163, v26, vcc
	v_lshlrev_b32_e32 v26, 2, v26
	ds_bpermute_b32 v26, v26, v25
	v_cvt_pk_bf16_f32 v28, v10, v11
	v_cvt_pk_bf16_f32 v29, v12, v13
	global_store_dwordx2 v[30:31], v[28:29], off offset:32
	s_and_saveexec_b64 s[10:11], s[4:5]
	s_cbranch_execz .LBB0_489
	v_lshlrev_b64 v[28:29], 5, v[18:19]
	v_lshl_add_u64 v[28:29], s[42:43], 0, v[28:29]
	s_waitcnt lgkmcnt(0)
	v_add_f32_e32 v25, v25, v26
	global_store_dword v[28:29], v25, off offset:16
